# GATE: removed two redundant compiler vmcnt waits that split the 8-load burst per trip (store-data WAR is a wait-state hazard on gfx950)
# baseline (speedup 1.0000x reference)
; __device__ __forceinline__ void gate_phase(const Ctx& c) {
;     ...
;     for (int it0 = c.gw; it0 < NIT; it0 += U * c.ngw) {
;         u32x4 yv[U], zv[U];
; #pragma unroll
;         for (int u = 0; u < U; ++u) {
;             const int it = it0 + u * c.ngw;
;             if (it < NIT) { const int row = it >> 2, col = (it & 3) * 512 + c.lane * 8;
;                 yv[u] = *(const u32x4*)(XBC + (size_t)row * CONVD + col); zv[u] = *(const u32x4*)(Z + (size_t)row * DIN + col); }
;             else { yv[u] = (u32x4){0u, 0u, 0u, 0u}; zv[u] = yv[u]; }
;         }
.LBB0_122:
	v_mov_b32_e32 v16, 0
	s_andn2_b64 vcc, exec, s[2:3]
	v_mov_b32_e32 v17, 0
	v_mov_b32_e32 v18, 0
	v_mov_b32_e32 v19, 0
	v_mov_b32_e32 v12, 0
	v_mov_b32_e32 v13, 0
	v_mov_b32_e32 v14, 0
	v_mov_b32_e32 v15, 0
	s_cbranch_vccnz .LBB0_124
	s_ashr_i32 s2, s19, 2
	s_ashr_i32 s3, s2, 31
	s_mul_i32 s18, s2, 0x1800
	s_mul_hi_i32 s11, s2, 0x1800
	s_add_u32 s20, s12, s18
	s_addc_u32 s21, s13, s11
	s_lshl_b64 s[2:3], s[2:3], 12
	s_add_u32 s2, s14, s2
	s_addc_u32 s3, s15, s3
	global_load_dwordx4 v[12:15], v0, s[20:21]
	global_load_dwordx4 v[16:19], v0, s[2:3]
